# P3: every unit's residual tile is C-init of the accumulators (first unit loaded inside the grid barrier, next unit right behind the previous unit's output stores); all out-proj epilogues store-only
# baseline (speedup 1.0000x reference)
;     __device__ __forceinline__ void operator()(const f32x4 (&acc)[2][2][4][2], const Unit& u, int wr, int wc, int fr, int fq) const {
;         const int row0 = u.pm * BM + wr * 64 + fr, col0 = u.pn * BM + wc * 32 + 4 * fq;
; #pragma unroll
;         for (int ai = 0; ai < 2; ++ai) {
;             f32x4 res[4][2][2];
; #pragma unroll
;             for (int m = 0; m < 4; ++m) { const size_t off = (size_t)(row0 + ai * HALF + m * 16) * ldc + col0;
; #pragma unroll
;                 for (int bj = 0; bj < 2; ++bj)
; #pragma unroll
;                     for (int n = 0; n < 2; ++n) res[m][bj][n] = *(const f32x4*)(base + off + bj * HALF + n * 16); }
.LBB0_443:
	s_or_b64 exec, exec, s[2:3]
	s_mov_b32 s101, 0
	s_cmpk_gt_i32 s82, 0x1ff
	s_cbranch_scc1 .Lp3_nopre
	s_mov_b32 s101, 1
	v_readlane_b32 s84, v254, 0
	v_readlane_b32 s85, v254, 1
	s_and_b32 s86, s82, 7
	s_lshl_b32 s86, s86, 3
	s_bfe_u32 s87, s82, 0x30003
	s_or_b32 s86, s86, s87
	s_lshr_b32 s87, s82, 6
	s_lshl_b32 s86, s86, 21
	s_lshl_b32 s87, s87, 10
	s_add_u32 s86, s86, s87
	v_lshrrev_b32_e32 v251, 8, v229
	v_lshlrev_b32_e32 v251, 6, v251
	v_and_b32_e32 v252, 15, v229
	v_or_b32_e32 v251, v251, v252
	v_lshlrev_b32_e32 v251, 13, v251
	v_bfe_u32 v252, v229, 6, 2
	v_lshlrev_b32_e32 v252, 5, v252
	v_bfe_u32 v253, v229, 4, 2
	v_lshl_or_b32 v252, v253, 2, v252
	v_lshl_add_u32 v251, v252, 2, v251
	v_add_u32_e32 v250, s86, v251
	s_add_u32 s88, s84, 0x140000
	s_addc_u32 s89, s85, 0
	s_nop 0
	global_load_dwordx4 v[236:239], v250, s[88:89] offset:576
	s_add_u32 s90, s84, 0x160000
	s_addc_u32 s91, s85, 0
	s_nop 0
	global_load_dwordx4 v[240:243], v250, s[90:91] offset:512
	global_load_dwordx4 v[244:247], v250, s[90:91] offset:576
	global_load_dwordx4 v[124:127], v250, s[84:85]
	global_load_dwordx4 v[120:123], v250, s[84:85] offset:64
	global_load_dwordx4 v[104:107], v250, s[84:85] offset:512
	global_load_dwordx4 v[96:99], v250, s[84:85] offset:576
	s_add_u32 s92, s84, 0x20000
	s_addc_u32 s93, s85, 0
	s_nop 0
	global_load_dwordx4 v[116:119], v250, s[92:93]
	global_load_dwordx4 v[112:115], v250, s[92:93] offset:64
	global_load_dwordx4 v[88:91], v250, s[92:93] offset:512
	global_load_dwordx4 v[84:87], v250, s[92:93] offset:576
	s_add_u32 s94, s84, 0x40000
	s_addc_u32 s95, s85, 0
	s_nop 0
	global_load_dwordx4 v[108:111], v250, s[94:95]
	global_load_dwordx4 v[100:103], v250, s[94:95] offset:64
	global_load_dwordx4 v[76:79], v250, s[94:95] offset:512
	global_load_dwordx4 v[72:75], v250, s[94:95] offset:576
	s_add_u32 s96, s84, 0x60000
	s_addc_u32 s97, s85, 0
	s_nop 0
	global_load_dwordx4 v[92:95], v250, s[96:97]
	global_load_dwordx4 v[80:83], v250, s[96:97] offset:64
	global_load_dwordx4 v[68:71], v250, s[96:97] offset:512
	global_load_dwordx4 v[64:67], v250, s[96:97] offset:576
	s_add_u32 s98, s84, 0x100000
	s_addc_u32 s99, s85, 0
	s_nop 0
	global_load_dwordx4 v[60:63], v250, s[98:99]
	global_load_dwordx4 v[56:59], v250, s[98:99] offset:64
	global_load_dwordx4 v[40:43], v250, s[98:99] offset:512
	global_load_dwordx4 v[32:35], v250, s[98:99] offset:576
	s_add_u32 s88, s84, 0x120000
	s_addc_u32 s89, s85, 0
	s_nop 0
	global_load_dwordx4 v[52:55], v250, s[88:89]
	global_load_dwordx4 v[48:51], v250, s[88:89] offset:64
	global_load_dwordx4 v[24:27], v250, s[88:89] offset:512
	global_load_dwordx4 v[20:23], v250, s[88:89] offset:576
	s_add_u32 s90, s84, 0x140000
	s_addc_u32 s91, s85, 0
	s_nop 0
	global_load_dwordx4 v[44:47], v250, s[90:91]
	global_load_dwordx4 v[36:39], v250, s[90:91] offset:64
	global_load_dwordx4 v[12:15], v250, s[90:91] offset:512
	s_add_u32 s92, s84, 0x160000
	s_addc_u32 s93, s85, 0
	s_nop 0
	global_load_dwordx4 v[28:31], v250, s[92:93]
	global_load_dwordx4 v[16:19], v250, s[92:93] offset:64

;     __host__ __device__ bool next(int i, Unit& u) const { if (lo + i >= hi) return false; return base.next(lo + i, u); }
;     __device__ __forceinline__ void operator()(const f32x4 (&acc)[2][2][4][2], const Unit& u, int wr, int wc, int fr, int fq) const {
;         const int row0 = u.pm * BM + wr * 64 + fr, col0 = u.pn * BM + wc * 32 + 4 * fq;
; #pragma unroll
;         for (int ai = 0; ai < 2; ++ai) {
;             f32x4 res[4][2][2];
; #pragma unroll
;             for (int m = 0; m < 4; ++m) { const size_t off = (size_t)(row0 + ai * HALF + m * 16) * ldc + col0;
; #pragma unroll
;                 for (int bj = 0; bj < 2; ++bj)
; #pragma unroll
;                     for (int n = 0; n < 2; ++n) res[m][bj][n] = *(const f32x4*)(base + off + bj * HALF + n * 16); }
;             asm volatile("" ::: "memory");
; #pragma unroll
;             for (int m = 0; m < 4; ++m) { const size_t off = (size_t)(row0 + ai * HALF + m * 16) * ldc + col0;
; #pragma unroll
;                 for (int bj = 0; bj < 2; ++bj)
; #pragma unroll
;                     for (int n = 0; n < 2; ++n) *(f32x4*)(out + off + bj * HALF + n * 16) = res[m][bj][n] + acc[ai][bj][m][n]; }
;             asm volatile("" ::: "memory");
;         }
;     }
; template <class Epi, class Sched, bool ALIGN_EPI = false, bool SP2 = false>
; __device__ __forceinline__ void gemm_phase(PG8_LAS unsigned char* lds, const Gemm g, const Sched& S, const Epi& E) {
;     ...
;     for (;;) {
;         const bool has_next = S.next(ui + 1, nxt);
;         const char* nA = has_next ? (const char*)g.A + (size_t)nxt.pm * tstep : cA; const char* nB = has_next ? (const char*)g.Bt + (size_t)nxt.pn * tstep : cB;
.Lp3_preloaded:
	s_waitcnt vmcnt(29)
	v_mov_b32_e32 v8, v236
	v_mov_b32_e32 v9, v237
	v_mov_b32_e32 v10, v238
	v_mov_b32_e32 v11, v239
	v_mov_b32_e32 v4, v240
	v_mov_b32_e32 v5, v241
	v_mov_b32_e32 v6, v242
	v_mov_b32_e32 v7, v243
	v_mov_b32_e32 v0, v244
	v_mov_b32_e32 v1, v245
	v_mov_b32_e32 v2, v246
	v_mov_b32_e32 v3, v247
	s_branch .LBB0_458
.Lp3_epi_pre:
	global_store_dwordx4 v250, v[124:127], s[70:71]
	global_store_dwordx4 v250, v[120:123], s[70:71] offset:64
	global_store_dwordx4 v250, v[104:107], s[70:71] offset:512
	global_store_dwordx4 v250, v[96:99], s[70:71] offset:576
	s_add_u32 s88, s70, 0x20000
	s_addc_u32 s89, s71, 0
	s_nop 0
	global_store_dwordx4 v250, v[116:119], s[88:89]
	global_store_dwordx4 v250, v[112:115], s[88:89] offset:64
	global_store_dwordx4 v250, v[88:91], s[88:89] offset:512
	global_store_dwordx4 v250, v[84:87], s[88:89] offset:576
	s_add_u32 s90, s70, 0x40000
	s_addc_u32 s91, s71, 0
	s_nop 0
	global_store_dwordx4 v250, v[108:111], s[90:91]
	global_store_dwordx4 v250, v[100:103], s[90:91] offset:64
	global_store_dwordx4 v250, v[76:79], s[90:91] offset:512
	global_store_dwordx4 v250, v[72:75], s[90:91] offset:576
	s_add_u32 s92, s70, 0x60000
	s_addc_u32 s93, s71, 0
	s_nop 0
	global_store_dwordx4 v250, v[92:95], s[92:93]
	global_store_dwordx4 v250, v[80:83], s[92:93] offset:64
	global_store_dwordx4 v250, v[68:71], s[92:93] offset:512
	global_store_dwordx4 v250, v[64:67], s[92:93] offset:576
	s_add_u32 s94, s70, 0x100000
	s_addc_u32 s95, s71, 0
	s_nop 0
	global_store_dwordx4 v250, v[60:63], s[94:95]
	global_store_dwordx4 v250, v[56:59], s[94:95] offset:64
	global_store_dwordx4 v250, v[40:43], s[94:95] offset:512
	global_store_dwordx4 v250, v[32:35], s[94:95] offset:576
	s_add_u32 s96, s70, 0x120000
	s_addc_u32 s97, s71, 0
	s_nop 0
	global_store_dwordx4 v250, v[52:55], s[96:97]
	global_store_dwordx4 v250, v[48:51], s[96:97] offset:64
	global_store_dwordx4 v250, v[24:27], s[96:97] offset:512
	global_store_dwordx4 v250, v[20:23], s[96:97] offset:576
	s_add_u32 s98, s70, 0x140000
	s_addc_u32 s99, s71, 0
	s_nop 0
	global_store_dwordx4 v250, v[44:47], s[98:99]
	global_store_dwordx4 v250, v[36:39], s[98:99] offset:64
	global_store_dwordx4 v250, v[12:15], s[98:99] offset:512
	global_store_dwordx4 v250, v[8:11], s[98:99] offset:576
	s_add_u32 s88, s70, 0x160000
	s_addc_u32 s89, s71, 0
	s_nop 0
	global_store_dwordx4 v250, v[28:31], s[88:89]
	global_store_dwordx4 v250, v[16:19], s[88:89] offset:64
	global_store_dwordx4 v250, v[4:7], s[88:89] offset:512
	global_store_dwordx4 v250, v[0:3], s[88:89] offset:576
	s_mov_b32 s101, 0
	s_cmp_lg_u64 s[0:1], 0
	s_cbranch_scc0 .Lp3_epi_nonext
	s_mov_b32 s101, 1
	s_lshl_b32 s86, s18, 21
	s_lshl_b32 s87, s16, 10
	s_add_u32 s86, s86, s87
	s_nop 1
	v_add_u32_e32 v250, s86, v251
	s_add_u32 s88, s84, 0x140000
	s_addc_u32 s89, s85, 0
	s_nop 0
	global_load_dwordx4 v[236:239], v250, s[88:89] offset:576
	s_add_u32 s90, s84, 0x160000
	s_addc_u32 s91, s85, 0
	s_nop 0
	global_load_dwordx4 v[240:243], v250, s[90:91] offset:512
	global_load_dwordx4 v[244:247], v250, s[90:91] offset:576
	global_load_dwordx4 v[124:127], v250, s[84:85]
	global_load_dwordx4 v[120:123], v250, s[84:85] offset:64
	global_load_dwordx4 v[104:107], v250, s[84:85] offset:512
	global_load_dwordx4 v[96:99], v250, s[84:85] offset:576
	s_add_u32 s92, s84, 0x20000
	s_addc_u32 s93, s85, 0
	s_nop 0
	global_load_dwordx4 v[116:119], v250, s[92:93]
	global_load_dwordx4 v[112:115], v250, s[92:93] offset:64
	global_load_dwordx4 v[88:91], v250, s[92:93] offset:512
	global_load_dwordx4 v[84:87], v250, s[92:93] offset:576
	s_add_u32 s94, s84, 0x40000
	s_addc_u32 s95, s85, 0
	s_nop 0
	global_load_dwordx4 v[108:111], v250, s[94:95]
	global_load_dwordx4 v[100:103], v250, s[94:95] offset:64
	global_load_dwordx4 v[76:79], v250, s[94:95] offset:512
	global_load_dwordx4 v[72:75], v250, s[94:95] offset:576
	s_add_u32 s96, s84, 0x60000
	s_addc_u32 s97, s85, 0
	s_nop 0
	global_load_dwordx4 v[92:95], v250, s[96:97]
	global_load_dwordx4 v[80:83], v250, s[96:97] offset:64
	global_load_dwordx4 v[68:71], v250, s[96:97] offset:512
	global_load_dwordx4 v[64:67], v250, s[96:97] offset:576
	s_add_u32 s98, s84, 0x100000
	s_addc_u32 s99, s85, 0
	s_nop 0
	global_load_dwordx4 v[60:63], v250, s[98:99]
	global_load_dwordx4 v[56:59], v250, s[98:99] offset:64
	global_load_dwordx4 v[40:43], v250, s[98:99] offset:512
	global_load_dwordx4 v[32:35], v250, s[98:99] offset:576
	s_add_u32 s88, s84, 0x120000
	s_addc_u32 s89, s85, 0
	s_nop 0
	global_load_dwordx4 v[52:55], v250, s[88:89]
	global_load_dwordx4 v[48:51], v250, s[88:89] offset:64
	global_load_dwordx4 v[24:27], v250, s[88:89] offset:512
	global_load_dwordx4 v[20:23], v250, s[88:89] offset:576
	s_add_u32 s90, s84, 0x140000
	s_addc_u32 s91, s85, 0
	s_nop 0
	global_load_dwordx4 v[44:47], v250, s[90:91]
	global_load_dwordx4 v[36:39], v250, s[90:91] offset:64
	global_load_dwordx4 v[12:15], v250, s[90:91] offset:512
	s_add_u32 s92, s84, 0x160000
	s_addc_u32 s93, s85, 0
	s_nop 0
	global_load_dwordx4 v[28:31], v250, s[92:93]
	global_load_dwordx4 v[16:19], v250, s[92:93] offset:64
.Lp3_epi_nonext:
	v_readlane_b32 s48, v254, 0
	v_readlane_b32 s49, v254, 1
	s_andn2_b64 vcc, exec, s[0:1]
	s_mov_b64 s[0:1], -1
	v_readlane_b32 s50, v254, 2
	v_readlane_b32 s51, v254, 3
	v_readlane_b32 s52, v254, 4
	v_readlane_b32 s53, v254, 5
	v_readlane_b32 s54, v254, 6
	v_readlane_b32 s55, v254, 7
	v_readlane_b32 s56, v254, 8
	v_readlane_b32 s57, v254, 9
	v_readlane_b32 s58, v254, 10
	v_readlane_b32 s59, v254, 11
	v_readlane_b32 s60, v254, 12
	v_readlane_b32 s61, v254, 13
	v_readlane_b32 s62, v254, 14
	v_readlane_b32 s63, v254, 15
	s_branch .Lp3_epi_tail
